# P5a q/k/gate epilogue: all 8 sum-of-squares loads issued at the epilogue top, per-row-group vmcnt waits dropped so stores of one group overlap the next
# speedup vs baseline: 1.0121x; 1.0121x over previous
; __device__ __forceinline__ unsigned cvt_pk_bf16(float lo, float hi) { unsigned r; asm volatile("v_cvt_pk_bf16_f32 %0, %1, %2" : "=v"(r) : "v"(lo), "v"(hi)); return r; }
;     __device__ __forceinline__ void operator()(const f32x4 (&acc)[2][2][4][2], const Unit& u, int wr, int wc, int fr, int fq) const {
;         const int row0 = u.pm * BM + wr * 64 + fr, colt = u.pn * BM, region = colt >> 10;
;         const float sc = (region == 0) ? qscale : 1.f;
;         bf16_t* base = QF + (size_t)region * ((size_t)16384 * 1024);
; #pragma unroll
;         for (int ai = 0; ai < 2; ++ai)
; #pragma unroll
;             for (int m = 0; m < 4; ++m) { const int row = row0 + ai * HALF + m * 16;
;                 const float rs = __builtin_amdgcn_rsqf(ssq[row] * (1.0f / 1024.0f) + 1e-6f) * sc;
;                 const int b = row >> 12, tl = row & 4095, tile = tl >> 5, r = tl & 31;
; #pragma unroll
;                 for (int bj = 0; bj < 2; ++bj) { const int cc = (colt & 1023) + bj * HALF + wc * 32 + 8 * fq, h = cc >> 6, d8 = cc & 63, bh = b * 16 + h;
;                     const f32x4 v0 = acc[ai][bj][m][0] * rs, v1 = acc[ai][bj][m][1] * rs;
;                     u32x4 w; w.x = cvt_pk_bf16(v0[0], v0[1]); w.y = cvt_pk_bf16(v0[2], v0[3]); w.z = cvt_pk_bf16(v1[0], v1[1]); w.w = cvt_pk_bf16(v1[2], v1[3]);
;                     if (region < 2) { const int ks = d8 >> 4, hh = (d8 >> 3) & 1;
;                         *(u32x4*)(base + ((size_t)(((bh * 128 + tile) * 4 + ks) * 64 + hh * 32 + r) << 3)) = w;
.LBB0_493:
	s_lshl_b32 s5, s24, 8
	s_add_i32 s17, s5, s48
	v_or_b32_e32 v144, s17, v162
	v_ashrrev_i32_e32 v145, 31, v144
	v_lshl_add_u64 v[146:147], v[144:145], 2, s[8:9]
	global_load_dword v148, v[146:147], off
	global_load_dword v237, v[146:147], off offset:64
	global_load_dword v238, v[146:147], off offset:128
	global_load_dword v239, v[146:147], off offset:192
	global_load_dword v240, v[146:147], off offset:512
	global_load_dword v241, v[146:147], off offset:576
	global_load_dword v242, v[146:147], off offset:640
	global_load_dword v243, v[146:147], off offset:704
	s_lshl_b32 s19, s4, 8
	s_ashr_i32 s26, s4, 2
	s_cmp_lt_u32 s4, 4
	s_cselect_b64 vcc, -1, 0
	s_ashr_i32 s27, s26, 31
	s_lshl_b64 s[4:5], s[26:27], 25
	s_add_u32 s24, s46, s4
	s_addc_u32 s25, s47, s5
	s_and_b32 s4, s19, 0x300
	s_or_b32 s4, s4, s49
	s_cmp_gt_i32 s26, 1
	s_cselect_b64 s[26:27], -1, 0
	s_lshr_b32 s19, s17, 5
	v_cndmask_b32_e32 v145, 1.0, v166, vcc
	s_ashr_i32 s5, s17, 8
	s_and_b32 s31, s19, 0x7e
	s_lshr_b32 s17, s4, 6
	s_and_b32 s4, s5, -16
	s_lshl_b32 s5, s31, 3
	s_mov_b64 s[28:29], -1
	s_and_b64 vcc, exec, s[26:27]
	s_or_b32 s30, s4, s17
	s_or_b32 s76, s5, s69
	s_waitcnt vmcnt(0)
	v_fmamk_f32 v148, v148, 0x3a800000, v165
	v_rsq_f32_e32 v148, v148
	s_nop 0
	v_mul_f32_e32 v148, v145, v148
	v_pk_mul_f32 v[168:169], v[122:123], v[148:149] op_sel_hi:[1,0]
	v_pk_mul_f32 v[122:123], v[120:121], v[148:149] op_sel_hi:[1,0]
	v_pk_mul_f32 v[126:127], v[126:127], v[148:149] op_sel_hi:[1,0]
	v_pk_mul_f32 v[124:125], v[124:125], v[148:149] op_sel_hi:[1,0]
	s_nop 0
	v_cvt_pk_bf16_f32 v120, v124, v125
	v_cvt_pk_bf16_f32 v121, v126, v127
	v_cvt_pk_bf16_f32 v122, v122, v123
	v_cvt_pk_bf16_f32 v123, v168, v169
	s_cbranch_vccz .LBB0_495
	s_lshl_b32 s5, s30, 10
	s_or_b32 s5, s76, s5
	v_or_b32_e32 v124, s5, v154
	v_lshl_or_b32 v124, v124, 6, v162
	v_ashrrev_i32_e32 v125, 31, v124
	v_lshl_add_u64 v[124:125], v[124:125], 3, s[24:25]
	global_store_dwordx2 v[124:125], v[120:121], off
	global_store_dwordx2 v[124:125], v[122:123], off offset:256
	s_mov_b64 s[28:29], 0

; __device__ __forceinline__ unsigned cvt_pk_bf16(float lo, float hi) { unsigned r; asm volatile("v_cvt_pk_bf16_f32 %0, %1, %2" : "=v"(r) : "v"(lo), "v"(hi)); return r; }
;     __device__ __forceinline__ void operator()(const f32x4 (&acc)[2][2][4][2], const Unit& u, int wr, int wc, int fr, int fq) const {
;     ...
;             for (int m = 0; m < 4; ++m) { const int row = row0 + ai * HALF + m * 16;
;                 const float rs = __builtin_amdgcn_rsqf(ssq[row] * (1.0f / 1024.0f) + 1e-6f) * sc;
;                 const int b = row >> 12, tl = row & 4095, tile = tl >> 5, r = tl & 31;
; #pragma unroll
;                 for (int bj = 0; bj < 2; ++bj) { const int cc = (colt & 1023) + bj * HALF + wc * 32 + 8 * fq, h = cc >> 6, d8 = cc & 63, bh = b * 16 + h;
;                     const f32x4 v0 = acc[ai][bj][m][0] * rs, v1 = acc[ai][bj][m][1] * rs;
;                     u32x4 w; w.x = cvt_pk_bf16(v0[0], v0[1]); w.y = cvt_pk_bf16(v0[2], v0[3]); w.z = cvt_pk_bf16(v1[0], v1[1]); w.w = cvt_pk_bf16(v1[2], v1[3]);
;                     if (region < 2) { const int ks = d8 >> 4, hh = (d8 >> 3) & 1;
;                         *(u32x4*)(base + ((size_t)(((bh * 128 + tile) * 4 + ks) * 64 + hh * 32 + r) << 3)) = w;
;                     } else { const int dt = d8 >> 5, g = (d8 >> 3) & 3; bf16_t* p = base + ((size_t)((((bh * 128 + tile) * 2 + dt) * 4 + g) * 64 + r) << 2);
;                         *(unsigned long long*)p = (unsigned long long)w.x | ((unsigned long long)w.y << 32);
;                         *(unsigned long long*)(p + 128) = (unsigned long long)w.z | ((unsigned long long)w.w << 32); } }
.LBB0_501:
	s_nop 0
	s_and_b64 vcc, exec, s[4:5]
	s_mov_b64 s[26:27], -1
	s_nop 0
	v_fmamk_f32 v112, v237, 0x3a800000, v165
	v_rsq_f32_e32 v112, v112
	s_nop 0
	v_mul_f32_e32 v112, v145, v112
	v_pk_mul_f32 v[114:115], v[106:107], v[112:113] op_sel_hi:[1,0]
	v_pk_mul_f32 v[106:107], v[104:105], v[112:113] op_sel_hi:[1,0]
	v_pk_mul_f32 v[110:111], v[110:111], v[112:113] op_sel_hi:[1,0]
	v_pk_mul_f32 v[108:109], v[108:109], v[112:113] op_sel_hi:[1,0]
	s_nop 0
	v_cvt_pk_bf16_f32 v104, v108, v109
	v_cvt_pk_bf16_f32 v105, v110, v111
	v_cvt_pk_bf16_f32 v106, v106, v107
	v_cvt_pk_bf16_f32 v107, v114, v115
	s_cbranch_vccnz .LBB0_503
	s_lshl_b32 s26, s30, 10
	s_or_b32 s26, s76, s26
	v_or_b32_e32 v108, s26, v154
	v_lshl_or_b32 v108, v108, 6, v158
	v_ashrrev_i32_e32 v109, 31, v108
	v_lshl_add_u64 v[108:109], v[108:109], 3, s[24:25]
	s_mov_b64 s[26:27], 0
	global_store_dwordx2 v[108:109], v[104:105], off
	global_store_dwordx2 v[108:109], v[106:107], off offset:256

; __device__ __forceinline__ unsigned cvt_pk_bf16(float lo, float hi) { unsigned r; asm volatile("v_cvt_pk_bf16_f32 %0, %1, %2" : "=v"(r) : "v"(lo), "v"(hi)); return r; }
;     __device__ __forceinline__ void operator()(const f32x4 (&acc)[2][2][4][2], const Unit& u, int wr, int wc, int fr, int fq) const {
;     ...
;             for (int m = 0; m < 4; ++m) { const int row = row0 + ai * HALF + m * 16;
;                 const float rs = __builtin_amdgcn_rsqf(ssq[row] * (1.0f / 1024.0f) + 1e-6f) * sc;
;                 const int b = row >> 12, tl = row & 4095, tile = tl >> 5, r = tl & 31;
; #pragma unroll
;                 for (int bj = 0; bj < 2; ++bj) { const int cc = (colt & 1023) + bj * HALF + wc * 32 + 8 * fq, h = cc >> 6, d8 = cc & 63, bh = b * 16 + h;
;                     const f32x4 v0 = acc[ai][bj][m][0] * rs, v1 = acc[ai][bj][m][1] * rs;
;                     u32x4 w; w.x = cvt_pk_bf16(v0[0], v0[1]); w.y = cvt_pk_bf16(v0[2], v0[3]); w.z = cvt_pk_bf16(v1[0], v1[1]); w.w = cvt_pk_bf16(v1[2], v1[3]);
;                     if (region < 2) { const int ks = d8 >> 4, hh = (d8 >> 3) & 1;
;                         *(u32x4*)(base + ((size_t)(((bh * 128 + tile) * 4 + ks) * 64 + hh * 32 + r) << 3)) = w;
;                     } else { const int dt = d8 >> 5, g = (d8 >> 3) & 3; bf16_t* p = base + ((size_t)((((bh * 128 + tile) * 2 + dt) * 4 + g) * 64 + r) << 2);
;                         *(unsigned long long*)p = (unsigned long long)w.x | ((unsigned long long)w.y << 32);
;                         *(unsigned long long*)(p + 128) = (unsigned long long)w.z | ((unsigned long long)w.w << 32); } }
.LBB0_509:
	s_nop 1
	v_or_b32_e32 v96, 32, v144
	v_ashrrev_i32_e32 v97, 31, v96
	v_lshl_add_u64 v[98:99], v[96:97], 2, s[8:9]
	s_nop 0
	s_and_b64 vcc, exec, s[4:5]
	s_mov_b64 s[26:27], -1
	s_nop 0
	v_fmamk_f32 v97, v238, 0x3a800000, v165
	v_rsq_f32_e32 v99, v97
	v_bfe_u32 v97, v96, 5, 7
	v_lshl_or_b32 v98, v97, 3, s58
	v_mul_f32_e32 v96, v145, v99
	v_pk_mul_f32 v[100:101], v[90:91], v[96:97] op_sel_hi:[1,0]
	v_pk_mul_f32 v[90:91], v[88:89], v[96:97] op_sel_hi:[1,0]
	v_pk_mul_f32 v[94:95], v[94:95], v[96:97] op_sel_hi:[1,0]
	v_pk_mul_f32 v[92:93], v[92:93], v[96:97] op_sel_hi:[1,0]
	s_nop 0
	v_cvt_pk_bf16_f32 v88, v92, v93
	v_cvt_pk_bf16_f32 v89, v94, v95
	v_cvt_pk_bf16_f32 v90, v90, v91
	v_cvt_pk_bf16_f32 v91, v100, v101
	s_cbranch_vccnz .LBB0_511
	s_lshl_b32 s26, s30, 10
	v_or3_b32 v92, v98, s26, v154
	v_lshl_or_b32 v92, v92, 6, v162
	v_ashrrev_i32_e32 v93, 31, v92
	v_lshl_add_u64 v[92:93], v[92:93], 3, s[24:25]
	s_mov_b64 s[26:27], 0
	global_store_dwordx2 v[92:93], v[88:89], off
	global_store_dwordx2 v[92:93], v[90:91], off offset:256

; __device__ __forceinline__ unsigned cvt_pk_bf16(float lo, float hi) { unsigned r; asm volatile("v_cvt_pk_bf16_f32 %0, %1, %2" : "=v"(r) : "v"(lo), "v"(hi)); return r; }
;     __device__ __forceinline__ void operator()(const f32x4 (&acc)[2][2][4][2], const Unit& u, int wr, int wc, int fr, int fq) const {
;     ...
;             for (int m = 0; m < 4; ++m) { const int row = row0 + ai * HALF + m * 16;
;                 const float rs = __builtin_amdgcn_rsqf(ssq[row] * (1.0f / 1024.0f) + 1e-6f) * sc;
;                 const int b = row >> 12, tl = row & 4095, tile = tl >> 5, r = tl & 31;
; #pragma unroll
;                 for (int bj = 0; bj < 2; ++bj) { const int cc = (colt & 1023) + bj * HALF + wc * 32 + 8 * fq, h = cc >> 6, d8 = cc & 63, bh = b * 16 + h;
;                     const f32x4 v0 = acc[ai][bj][m][0] * rs, v1 = acc[ai][bj][m][1] * rs;
;                     u32x4 w; w.x = cvt_pk_bf16(v0[0], v0[1]); w.y = cvt_pk_bf16(v0[2], v0[3]); w.z = cvt_pk_bf16(v1[0], v1[1]); w.w = cvt_pk_bf16(v1[2], v1[3]);
;                     if (region < 2) { const int ks = d8 >> 4, hh = (d8 >> 3) & 1;
;                         *(u32x4*)(base + ((size_t)(((bh * 128 + tile) * 4 + ks) * 64 + hh * 32 + r) << 3)) = w;
;                     } else { const int dt = d8 >> 5, g = (d8 >> 3) & 3; bf16_t* p = base + ((size_t)((((bh * 128 + tile) * 2 + dt) * 4 + g) * 64 + r) << 2);
;                         *(unsigned long long*)p = (unsigned long long)w.x | ((unsigned long long)w.y << 32);
;                         *(unsigned long long*)(p + 128) = (unsigned long long)w.z | ((unsigned long long)w.w << 32); } }
.LBB0_517:
	s_nop 1
	v_or_b32_e32 v80, 48, v144
	v_ashrrev_i32_e32 v81, 31, v80
	v_lshl_add_u64 v[82:83], v[80:81], 2, s[8:9]
	s_nop 0
	s_and_b64 vcc, exec, s[4:5]
	s_mov_b64 s[26:27], -1
	s_nop 0
	v_fmamk_f32 v81, v239, 0x3a800000, v165
	v_rsq_f32_e32 v83, v81
	v_bfe_u32 v81, v80, 5, 7
	v_lshl_or_b32 v82, v81, 3, s58
	v_mul_f32_e32 v80, v145, v83
	v_pk_mul_f32 v[84:85], v[74:75], v[80:81] op_sel_hi:[1,0]
	v_pk_mul_f32 v[74:75], v[72:73], v[80:81] op_sel_hi:[1,0]
	v_pk_mul_f32 v[78:79], v[78:79], v[80:81] op_sel_hi:[1,0]
	v_pk_mul_f32 v[76:77], v[76:77], v[80:81] op_sel_hi:[1,0]
	s_nop 0
	v_cvt_pk_bf16_f32 v72, v76, v77
	v_cvt_pk_bf16_f32 v73, v78, v79
	v_cvt_pk_bf16_f32 v74, v74, v75
	v_cvt_pk_bf16_f32 v75, v84, v85
	s_cbranch_vccnz .LBB0_519
	s_lshl_b32 s26, s30, 10
	v_or3_b32 v76, v82, s26, v154
	v_lshl_or_b32 v76, v76, 6, v158
	v_ashrrev_i32_e32 v77, 31, v76
	v_lshl_add_u64 v[76:77], v[76:77], 3, s[24:25]
	s_mov_b64 s[26:27], 0
	global_store_dwordx2 v[76:77], v[72:73], off
	global_store_dwordx2 v[76:77], v[74:75], off offset:256

; __device__ __forceinline__ unsigned cvt_pk_bf16(float lo, float hi) { unsigned r; asm volatile("v_cvt_pk_bf16_f32 %0, %1, %2" : "=v"(r) : "v"(lo), "v"(hi)); return r; }
;     __device__ __forceinline__ void operator()(const f32x4 (&acc)[2][2][4][2], const Unit& u, int wr, int wc, int fr, int fq) const {
;     ...
;             for (int m = 0; m < 4; ++m) { const int row = row0 + ai * HALF + m * 16;
;                 const float rs = __builtin_amdgcn_rsqf(ssq[row] * (1.0f / 1024.0f) + 1e-6f) * sc;
;                 const int b = row >> 12, tl = row & 4095, tile = tl >> 5, r = tl & 31;
; #pragma unroll
;                 for (int bj = 0; bj < 2; ++bj) { const int cc = (colt & 1023) + bj * HALF + wc * 32 + 8 * fq, h = cc >> 6, d8 = cc & 63, bh = b * 16 + h;
;                     const f32x4 v0 = acc[ai][bj][m][0] * rs, v1 = acc[ai][bj][m][1] * rs;
;                     u32x4 w; w.x = cvt_pk_bf16(v0[0], v0[1]); w.y = cvt_pk_bf16(v0[2], v0[3]); w.z = cvt_pk_bf16(v1[0], v1[1]); w.w = cvt_pk_bf16(v1[2], v1[3]);
;                     if (region < 2) { const int ks = d8 >> 4, hh = (d8 >> 3) & 1;
;                         *(u32x4*)(base + ((size_t)(((bh * 128 + tile) * 4 + ks) * 64 + hh * 32 + r) << 3)) = w;
;                     } else { const int dt = d8 >> 5, g = (d8 >> 3) & 3; bf16_t* p = base + ((size_t)((((bh * 128 + tile) * 2 + dt) * 4 + g) * 64 + r) << 2);
;                         *(unsigned long long*)p = (unsigned long long)w.x | ((unsigned long long)w.y << 32);
;                         *(unsigned long long*)(p + 128) = (unsigned long long)w.z | ((unsigned long long)w.w << 32); } }
.LBB0_525:
	s_nop 0
	s_nop 0
	v_add_u32_e32 v65, 0x80, v144
	v_ashrrev_i32_e32 v66, 8, v65
	v_lshrrev_b32_e32 v65, 5, v65
	v_and_b32_e32 v67, -16, v66
	v_and_b32_e32 v65, 0x7e, v65
	v_or_b32_e32 v68, s17, v67
	s_mov_b64 s[26:27], -1
	s_and_b64 vcc, exec, s[4:5]
	v_lshl_or_b32 v66, v65, 3, s69
	s_nop 0
	v_fmamk_f32 v64, v240, 0x3a800000, v165
	v_rsq_f32_e32 v64, v64
	s_nop 0
	v_mul_f32_e32 v64, v145, v64
	v_pk_mul_f32 v[60:61], v[60:61], v[64:65] op_sel_hi:[1,0]
	v_pk_mul_f32 v[70:71], v[58:59], v[64:65] op_sel_hi:[1,0]
	v_pk_mul_f32 v[58:59], v[56:57], v[64:65] op_sel_hi:[1,0]
	v_cvt_pk_bf16_f32 v56, v60, v61
	v_lshlrev_b32_e32 v61, 10, v68
	v_pk_mul_f32 v[62:63], v[62:63], v[64:65] op_sel_hi:[1,0]
	s_nop 0
	v_cvt_pk_bf16_f32 v57, v62, v63
	v_cvt_pk_bf16_f32 v58, v58, v59
	v_cvt_pk_bf16_f32 v59, v70, v71
	s_cbranch_vccnz .LBB0_527
	v_or3_b32 v60, v66, v61, v154
	v_lshl_or_b32 v62, v60, 6, v162
	v_ashrrev_i32_e32 v63, 31, v62
	v_lshl_add_u64 v[62:63], v[62:63], 3, s[24:25]
	s_mov_b64 s[26:27], 0
	global_store_dwordx2 v[62:63], v[56:57], off
	global_store_dwordx2 v[62:63], v[58:59], off offset:256

; __device__ __forceinline__ unsigned cvt_pk_bf16(float lo, float hi) { unsigned r; asm volatile("v_cvt_pk_bf16_f32 %0, %1, %2" : "=v"(r) : "v"(lo), "v"(hi)); return r; }
;     __device__ __forceinline__ void operator()(const f32x4 (&acc)[2][2][4][2], const Unit& u, int wr, int wc, int fr, int fq) const {
;     ...
;             for (int m = 0; m < 4; ++m) { const int row = row0 + ai * HALF + m * 16;
;                 const float rs = __builtin_amdgcn_rsqf(ssq[row] * (1.0f / 1024.0f) + 1e-6f) * sc;
;                 const int b = row >> 12, tl = row & 4095, tile = tl >> 5, r = tl & 31;
; #pragma unroll
;                 for (int bj = 0; bj < 2; ++bj) { const int cc = (colt & 1023) + bj * HALF + wc * 32 + 8 * fq, h = cc >> 6, d8 = cc & 63, bh = b * 16 + h;
;                     const f32x4 v0 = acc[ai][bj][m][0] * rs, v1 = acc[ai][bj][m][1] * rs;
;                     u32x4 w; w.x = cvt_pk_bf16(v0[0], v0[1]); w.y = cvt_pk_bf16(v0[2], v0[3]); w.z = cvt_pk_bf16(v1[0], v1[1]); w.w = cvt_pk_bf16(v1[2], v1[3]);
;                     if (region < 2) { const int ks = d8 >> 4, hh = (d8 >> 3) & 1;
;                         *(u32x4*)(base + ((size_t)(((bh * 128 + tile) * 4 + ks) * 64 + hh * 32 + r) << 3)) = w;
;                     } else { const int dt = d8 >> 5, g = (d8 >> 3) & 3; bf16_t* p = base + ((size_t)((((bh * 128 + tile) * 2 + dt) * 4 + g) * 64 + r) << 2);
;                         *(unsigned long long*)p = (unsigned long long)w.x | ((unsigned long long)w.y << 32);
;                         *(unsigned long long*)(p + 128) = (unsigned long long)w.z | ((unsigned long long)w.w << 32); } }
.LBB0_533:
	s_nop 0
	s_nop 0
	v_add_u32_e32 v49, 0x90, v144
	v_lshrrev_b32_e32 v49, 5, v49
	v_and_b32_e32 v49, 0x7e, v49
	s_and_b64 vcc, exec, s[4:5]
	v_lshl_or_b32 v50, v49, 3, s69
	s_mov_b64 s[26:27], -1
	s_nop 0
	v_fmamk_f32 v48, v241, 0x3a800000, v165
	v_rsq_f32_e32 v48, v48
	s_nop 0
	v_mul_f32_e32 v48, v145, v48
	v_pk_mul_f32 v[54:55], v[42:43], v[48:49] op_sel_hi:[1,0]
	v_pk_mul_f32 v[42:43], v[40:41], v[48:49] op_sel_hi:[1,0]
	v_pk_mul_f32 v[46:47], v[46:47], v[48:49] op_sel_hi:[1,0]
	v_pk_mul_f32 v[44:45], v[44:45], v[48:49] op_sel_hi:[1,0]
	s_nop 0
	v_cvt_pk_bf16_f32 v40, v44, v45
	v_cvt_pk_bf16_f32 v41, v46, v47
	v_cvt_pk_bf16_f32 v42, v42, v43
	v_cvt_pk_bf16_f32 v43, v54, v55
	s_cbranch_vccnz .LBB0_535
	v_or3_b32 v44, v50, v61, v154
	v_lshl_or_b32 v44, v44, 6, v158
	v_ashrrev_i32_e32 v45, 31, v44
	v_lshl_add_u64 v[44:45], v[44:45], 3, s[24:25]
	s_mov_b64 s[26:27], 0
	global_store_dwordx2 v[44:45], v[40:41], off
	global_store_dwordx2 v[44:45], v[42:43], off offset:256

; __device__ __forceinline__ unsigned cvt_pk_bf16(float lo, float hi) { unsigned r; asm volatile("v_cvt_pk_bf16_f32 %0, %1, %2" : "=v"(r) : "v"(lo), "v"(hi)); return r; }
;     __device__ __forceinline__ void operator()(const f32x4 (&acc)[2][2][4][2], const Unit& u, int wr, int wc, int fr, int fq) const {
;     ...
;             for (int m = 0; m < 4; ++m) { const int row = row0 + ai * HALF + m * 16;
;                 const float rs = __builtin_amdgcn_rsqf(ssq[row] * (1.0f / 1024.0f) + 1e-6f) * sc;
;                 const int b = row >> 12, tl = row & 4095, tile = tl >> 5, r = tl & 31;
; #pragma unroll
;                 for (int bj = 0; bj < 2; ++bj) { const int cc = (colt & 1023) + bj * HALF + wc * 32 + 8 * fq, h = cc >> 6, d8 = cc & 63, bh = b * 16 + h;
;                     const f32x4 v0 = acc[ai][bj][m][0] * rs, v1 = acc[ai][bj][m][1] * rs;
;                     u32x4 w; w.x = cvt_pk_bf16(v0[0], v0[1]); w.y = cvt_pk_bf16(v0[2], v0[3]); w.z = cvt_pk_bf16(v1[0], v1[1]); w.w = cvt_pk_bf16(v1[2], v1[3]);
;                     if (region < 2) { const int ks = d8 >> 4, hh = (d8 >> 3) & 1;
;                         *(u32x4*)(base + ((size_t)(((bh * 128 + tile) * 4 + ks) * 64 + hh * 32 + r) << 3)) = w;
;                     } else { const int dt = d8 >> 5, g = (d8 >> 3) & 3; bf16_t* p = base + ((size_t)((((bh * 128 + tile) * 2 + dt) * 4 + g) * 64 + r) << 2);
;                         *(unsigned long long*)p = (unsigned long long)w.x | ((unsigned long long)w.y << 32);
;                         *(unsigned long long*)(p + 128) = (unsigned long long)w.z | ((unsigned long long)w.w << 32); } }
.LBB0_541:
	s_nop 0
	s_nop 0
	v_add_u32_e32 v33, 0xa0, v144
	v_bfe_u32 v33, v33, 5, 7
	s_and_b64 vcc, exec, s[4:5]
	v_lshl_or_b32 v34, v33, 3, s69
	s_mov_b64 s[26:27], -1
	s_nop 0
	v_fmamk_f32 v32, v242, 0x3a800000, v165
	v_rsq_f32_e32 v32, v32
	s_nop 0
	v_mul_f32_e32 v32, v145, v32
	v_pk_mul_f32 v[36:37], v[26:27], v[32:33] op_sel_hi:[1,0]
	v_pk_mul_f32 v[26:27], v[24:25], v[32:33] op_sel_hi:[1,0]
	v_pk_mul_f32 v[30:31], v[30:31], v[32:33] op_sel_hi:[1,0]
	v_pk_mul_f32 v[28:29], v[28:29], v[32:33] op_sel_hi:[1,0]
	s_nop 0
	v_cvt_pk_bf16_f32 v24, v28, v29
	v_cvt_pk_bf16_f32 v25, v30, v31
	v_cvt_pk_bf16_f32 v26, v26, v27
	v_cvt_pk_bf16_f32 v27, v36, v37
	s_cbranch_vccnz .LBB0_543
	v_or3_b32 v28, v34, v61, v154
	v_lshl_or_b32 v28, v28, 6, v162
	v_ashrrev_i32_e32 v29, 31, v28
	v_lshl_add_u64 v[28:29], v[28:29], 3, s[24:25]
	s_mov_b64 s[26:27], 0
	global_store_dwordx2 v[28:29], v[24:25], off
	global_store_dwordx2 v[28:29], v[26:27], off offset:256

; __device__ __forceinline__ unsigned cvt_pk_bf16(float lo, float hi) { unsigned r; asm volatile("v_cvt_pk_bf16_f32 %0, %1, %2" : "=v"(r) : "v"(lo), "v"(hi)); return r; }
;     __device__ __forceinline__ void operator()(const f32x4 (&acc)[2][2][4][2], const Unit& u, int wr, int wc, int fr, int fq) const {
;     ...
;             for (int m = 0; m < 4; ++m) { const int row = row0 + ai * HALF + m * 16;
;                 const float rs = __builtin_amdgcn_rsqf(ssq[row] * (1.0f / 1024.0f) + 1e-6f) * sc;
;                 const int b = row >> 12, tl = row & 4095, tile = tl >> 5, r = tl & 31;
; #pragma unroll
;                 for (int bj = 0; bj < 2; ++bj) { const int cc = (colt & 1023) + bj * HALF + wc * 32 + 8 * fq, h = cc >> 6, d8 = cc & 63, bh = b * 16 + h;
;                     const f32x4 v0 = acc[ai][bj][m][0] * rs, v1 = acc[ai][bj][m][1] * rs;
;                     u32x4 w; w.x = cvt_pk_bf16(v0[0], v0[1]); w.y = cvt_pk_bf16(v0[2], v0[3]); w.z = cvt_pk_bf16(v1[0], v1[1]); w.w = cvt_pk_bf16(v1[2], v1[3]);
;                     if (region < 2) { const int ks = d8 >> 4, hh = (d8 >> 3) & 1;
;                         *(u32x4*)(base + ((size_t)(((bh * 128 + tile) * 4 + ks) * 64 + hh * 32 + r) << 3)) = w;
;                     } else { const int dt = d8 >> 5, g = (d8 >> 3) & 3; bf16_t* p = base + ((size_t)((((bh * 128 + tile) * 2 + dt) * 4 + g) * 64 + r) << 2);
;                         *(unsigned long long*)p = (unsigned long long)w.x | ((unsigned long long)w.y << 32);
;                         *(unsigned long long*)(p + 128) = (unsigned long long)w.z | ((unsigned long long)w.w << 32); } }
.LBB0_549:
	s_nop 0
	s_nop 0
	v_add_u32_e32 v17, 0xb0, v144
	v_bfe_u32 v17, v17, 5, 7
	s_and_b64 vcc, exec, s[4:5]
	v_lshl_or_b32 v18, v17, 3, s69
	s_mov_b64 s[26:27], -1
	s_nop 0
	v_fmamk_f32 v16, v243, 0x3a800000, v165
	v_rsq_f32_e32 v16, v16
	s_nop 0
	v_mul_f32_e32 v16, v145, v16
	v_pk_mul_f32 v[20:21], v[10:11], v[16:17] op_sel_hi:[1,0]
	v_pk_mul_f32 v[10:11], v[8:9], v[16:17] op_sel_hi:[1,0]
	v_pk_mul_f32 v[14:15], v[14:15], v[16:17] op_sel_hi:[1,0]
	v_pk_mul_f32 v[12:13], v[12:13], v[16:17] op_sel_hi:[1,0]
	s_nop 0
	v_cvt_pk_bf16_f32 v8, v12, v13
	v_cvt_pk_bf16_f32 v9, v14, v15
	v_cvt_pk_bf16_f32 v10, v10, v11
	v_cvt_pk_bf16_f32 v11, v20, v21
	s_cbranch_vccnz .LBB0_551
	v_or3_b32 v12, v18, v61, v154
	v_lshl_or_b32 v12, v12, 6, v158
	v_ashrrev_i32_e32 v13, 31, v12
	v_lshl_add_u64 v[12:13], v[12:13], 3, s[24:25]
	s_mov_b64 s[26:27], 0
	global_store_dwordx2 v[12:13], v[8:9], off
	global_store_dwordx2 v[12:13], v[10:11], off offset:256
